# added on the static-priority version: static priority raise for waves 4-7 during the attention phases
# speedup vs baseline: 1.0048x; 1.0048x over previous
.LBB0_352:
	s_cmp_lt_u32 s32, 0x100
	s_cbranch_scc1 .Latt_sprio
	s_setprio 1

.LBB0_630:
	s_setprio 0
	s_waitcnt vmcnt(0)
	s_barrier
	s_mov_b64 s[4:5], exec
	v_readlane_b32 s78, v254, 46
	v_readlane_b32 s80, v254, 59
	v_readlane_b32 s79, v254, 47
	v_readlane_b32 s81, v254, 60
	v_readlane_b32 s84, v255, 0
	v_readlane_b32 s90, v255, 2
	v_readlane_b32 s74, v255, 11
	s_and_b64 s[2:3], s[4:5], s[72:73]
	v_readlane_b32 s62, v252, 36
	v_readlane_b32 s63, v252, 37
	v_readlane_b32 s76, v254, 58
	v_readlane_b32 s77, v254, 61
	v_readlane_b32 s79, v254, 62
	v_readlane_b32 s82, v254, 63
	v_readlane_b32 s85, v255, 1
	v_readlane_b32 s91, v255, 3
	s_mov_b32 s64, 0x200000
	s_movk_i32 s65, 0x7fff
	s_mov_b32 s66, 0xffff0000
	s_mov_b32 s81, 0xbfb8aa3b
	s_movk_i32 s83, 0xdf
	s_movk_i32 s95, 0xef
	s_movk_i32 s96, 0xff
	s_mov_b64 s[70:71], 0x4000
	v_readlane_b32 s75, v255, 12
	s_mov_b64 exec, s[2:3]
	s_cbranch_execz .LBB0_682
	v_readlane_b32 s0, v254, 35
	s_waitcnt vmcnt(0) expcnt(0) lgkmcnt(0)
	s_nop 0
	v_mov_b32_e32 v0, s0
	ds_read_b32 v3, v0
	v_readlane_b32 s0, v254, 36
	s_waitcnt lgkmcnt(0)
	v_cmp_ne_u32_e32 vcc, 0, v3
	v_mov_b32_e32 v0, s0
	ds_read_b32 v2, v0
	s_cbranch_vccnz .LBB0_646
	s_mov_b32 s0, 1
	s_branch .LBB0_634
